# out-proj k-loop also switched to scalar M0 + running source addresses (all three GEMM loops now)
# speedup vs baseline: 1.0572x; 1.0026x over previous
; template <int EPI>
; DI void gemm_tile(const GemmArgs& ga, const EpiArgs& ea, int m0, int n0, char* lds) {
;     ...
;   const bf16_t* gsrc[6];
;   int ldsoff[6];
; #pragma unroll
;   for (int i = 0; i < 6; ++i) {
;     const int pi = w * 6 + i;
;     if (pi < 16) {
;       const int row = pi * 16 + prow;
;       gsrc[i] = ga.A + (size_t)(m0 + row) * ga.lda + swz64(row, pch) * 8;
;       ldsoff[i] = pi * 1024 + lane * 16;
;     } else {
;       const int row = (pi - 16) * 16 + prow;
;       gsrc[i] = ga.Bt + (size_t)(n0 + row) * K + swz64(row, pch) * 8;
;       ldsoff[i] = pi * 1024 + lane * 16;
;     }
;   }
;   auto dma = [&](int kt, int buf) {
;     const int k0 = kt << 5;
;     const int ac = ga.mix ? mixcol(k0) : k0;
;     char* base = lds + buf * 24576;
; #pragma unroll
;     for (int i = 0; i < 6; ++i) {
;       const int pi = w * 6 + i;
;       __builtin_amdgcn_global_load_lds((const unsigned*)(gsrc[i] + ((pi < 16) ? ac : k0)), (unsigned*)(base + ldsoff[i]), 16, 0, 0);
;     }
;   };
;   __syncthreads();
;   dma(0, 0);
;   if (nk > 1) dma(1, 1);
.LBB0_1516:
	v_mov_b32_e32 v142, v172
	s_lshl_b32 s22, s8, 7
	v_bfe_u32 v4, v142, 2, 4
	v_and_b32_e32 v0, 12, v4
	v_lshrrev_b32_e64 v0, v0, s34
	v_xor_b32_e32 v0, v0, v142
	s_add_i32 s0, s22, 0xffffff00
	v_lshlrev_b32_e32 v0, 4, v0
	v_ashrrev_i32_e32 v8, 6, v142
	v_or_b32_e32 v6, s0, v4
	v_and_b32_e32 v0, 48, v0
	s_movk_i32 s0, 0x60
	v_lshl_add_u64 v[2:3], s[6:7], 0, v[0:1]
	v_cmp_gt_i32_e32 vcc, 3, v8
	v_cmp_lt_i32_e64 s[36:37], 2, v8
	v_mul_lo_u32 v7, v8, s0
	s_and_saveexec_b64 s[0:1], s[36:37]
	s_xor_b64 s[0:1], exec, s[0:1]
	v_add_u32_e32 v10, v6, v7
	v_ashrrev_i32_e32 v11, 31, v10
	v_lshlrev_b64 v[10:11], 12, v[10:11]
	v_lshl_add_u64 v[130:131], v[2:3], 0, v[10:11]
	s_or_saveexec_b64 s[0:1], s[0:1]
	s_lshl_b32 s23, s23, 8
	v_or_b32_e32 v9, s23, v4
	v_lshl_add_u64 v[4:5], s[78:79], 0, v[0:1]
	s_xor_b64 exec, exec, s[0:1]
	v_add_u32_e32 v0, v9, v7
	v_mad_i64_i32 v[130:131], s[26:27], v0, s35, v[4:5]
	s_or_b64 exec, exec, s[0:1]
	v_mul_lo_u32 v7, v8, 6
	v_or_b32_e32 v0, 1, v7
	v_cmp_gt_i32_e64 s[0:1], 16, v0
	v_cmp_lt_i32_e64 s[38:39], 15, v0
	v_lshlrev_b32_e32 v10, 4, v0
	s_and_saveexec_b64 s[26:27], s[38:39]
	s_xor_b64 s[26:27], exec, s[26:27]
	v_add_u32_e32 v10, v10, v6
	v_ashrrev_i32_e32 v11, 31, v10
	v_lshlrev_b64 v[10:11], 12, v[10:11]
	v_lshl_add_u64 v[132:133], v[2:3], 0, v[10:11]
	s_andn2_saveexec_b64 s[26:27], s[26:27]
	v_add_u32_e32 v10, v10, v9
	v_mad_i64_i32 v[132:133], s[28:29], v10, s35, v[4:5]
	s_or_b64 exec, exec, s[26:27]
	v_add_u32_e32 v10, 2, v7
	v_lshlrev_b32_e32 v11, 4, v10
	s_and_saveexec_b64 s[26:27], s[36:37]
	s_xor_b64 s[26:27], exec, s[26:27]
	v_add_u32_e32 v12, v11, v6
	v_ashrrev_i32_e32 v13, 31, v12
	v_lshlrev_b64 v[12:13], 12, v[12:13]
	v_lshl_add_u64 v[134:135], v[2:3], 0, v[12:13]
	s_andn2_saveexec_b64 s[26:27], s[26:27]
	v_add_u32_e32 v11, v11, v9
	v_mad_i64_i32 v[134:135], s[28:29], v11, s35, v[4:5]
	s_or_b64 exec, exec, s[26:27]
	v_add_u32_e32 v11, 3, v7
	v_lshlrev_b32_e32 v12, 4, v11
	s_and_saveexec_b64 s[26:27], s[36:37]
	s_xor_b64 s[26:27], exec, s[26:27]
	v_add_u32_e32 v12, v12, v6
	v_ashrrev_i32_e32 v13, 31, v12
	v_lshlrev_b64 v[12:13], 12, v[12:13]
	v_lshl_add_u64 v[136:137], v[2:3], 0, v[12:13]
	s_andn2_saveexec_b64 s[26:27], s[26:27]
	v_add_u32_e32 v12, v12, v9
	v_mad_i64_i32 v[136:137], s[28:29], v12, s35, v[4:5]
	s_or_b64 exec, exec, s[26:27]
	v_add_u32_e32 v12, 4, v7
	v_cmp_gt_i32_e64 s[36:37], 2, v8
	v_cmp_lt_i32_e64 s[38:39], 1, v8
	v_lshlrev_b32_e32 v13, 4, v12
	s_and_saveexec_b64 s[26:27], s[38:39]
	s_xor_b64 s[26:27], exec, s[26:27]
	v_add_u32_e32 v14, v13, v6
	v_ashrrev_i32_e32 v15, 31, v14
	v_lshlrev_b64 v[14:15], 12, v[14:15]
	v_lshl_add_u64 v[138:139], v[2:3], 0, v[14:15]
	s_andn2_saveexec_b64 s[26:27], s[26:27]
	v_add_u32_e32 v13, v13, v9
	v_mad_i64_i32 v[138:139], s[28:29], v13, s35, v[4:5]
	s_or_b64 exec, exec, s[26:27]
	v_add_u32_e32 v13, 5, v7
	v_lshlrev_b32_e32 v14, 4, v13
	s_and_saveexec_b64 s[26:27], s[38:39]
	s_xor_b64 s[26:27], exec, s[26:27]
	v_add_u32_e32 v4, v14, v6
	v_ashrrev_i32_e32 v5, 31, v4
	v_lshlrev_b64 v[4:5], 12, v[4:5]
	v_lshl_add_u64 v[140:141], v[2:3], 0, v[4:5]
	s_or_saveexec_b64 s[26:27], s[26:27]
	v_mov_b64_e32 v[6:7], 0
	v_mov_b64_e32 v[2:3], 32
	s_xor_b64 exec, exec, s[26:27]
	v_add_u32_e32 v2, v14, v9
	v_mad_i64_i32 v[140:141], s[28:29], v2, s35, v[4:5]
	v_mov_b64_e32 v[6:7], 0x200
	v_mov_b64_e32 v[2:3], 0x220
	s_or_b64 exec, exec, s[26:27]
	v_and_b32_e32 v143, 63, v142
	v_lshlrev_b32_e32 v3, 4, v143
	s_movk_i32 s9, 0x1800
	v_lshl_or_b32 v158, v0, 10, v3
	v_mul_lo_u32 v0, v8, s9
	v_or_b32_e32 v159, v0, v3
	v_lshl_or_b32 v147, v12, 10, v3
	v_lshl_or_b32 v156, v11, 10, v3
	v_lshl_or_b32 v157, v10, 10, v3
	v_lshl_or_b32 v160, v13, 10, v3
	v_add_u32_e32 v3, 16, v159
	v_readfirstlane_b32 s101, v159
	v_cndmask_b32_e32 v0, 0, v186, vcc
	v_readfirstlane_b32 s27, v3
	v_lshl_add_u64 v[4:5], v[130:131], 0, v[0:1]
	s_mov_b32 m0, s27
	v_add_u32_e32 v7, 16, v158
	v_and_b32_e32 v144, 1, v8
	s_barrier
	global_load_lds_dwordx4 v[4:5], off
	v_cndmask_b32_e64 v4, 0, v186, s[0:1]
	v_mov_b32_e32 v5, v1
	v_readfirstlane_b32 s27, v7
	v_add_u32_e32 v8, 16, v157
	v_lshl_add_u64 v[4:5], v[132:133], 0, v[4:5]
	s_mov_b32 m0, s27
	v_readfirstlane_b32 s27, v8
	global_load_lds_dwordx4 v[4:5], off
	v_lshl_add_u64 v[4:5], v[134:135], 0, v[0:1]
	s_mov_b32 m0, s27
	v_add_u32_e32 v9, 16, v156
	global_load_lds_dwordx4 v[4:5], off
	v_lshl_add_u64 v[4:5], v[136:137], 0, v[0:1]
	v_readfirstlane_b32 s27, v9
	v_lshlrev_b32_e32 v0, 1, v6
	v_add_u32_e32 v6, 16, v147
	s_mov_b32 m0, s27
	v_readfirstlane_b32 s27, v6
	v_add_u32_e32 v10, 16, v160
	global_load_lds_dwordx4 v[4:5], off
	v_lshl_add_u64 v[4:5], v[138:139], 0, v[0:1]
	s_mov_b32 m0, s27
	v_readfirstlane_b32 s27, v10
	v_add_u32_e32 v3, 0x6000, v3
	global_load_lds_dwordx4 v[4:5], off
	v_lshl_add_u64 v[4:5], v[140:141], 0, v[0:1]
	s_mov_b32 m0, s27
	v_cndmask_b32_e32 v0, 64, v187, vcc
	v_readfirstlane_b32 s28, v3
	global_load_lds_dwordx4 v[4:5], off
	v_lshl_add_u64 v[4:5], v[130:131], 0, v[0:1]
	s_mov_b32 m0, s28
	v_add_u32_e32 v3, 0x6000, v7
	global_load_lds_dwordx4 v[4:5], off
	v_cndmask_b32_e64 v4, 64, v187, s[0:1]
	v_mov_b32_e32 v5, v1
	v_readfirstlane_b32 s28, v3
	v_add_u32_e32 v3, 0x6000, v8
	v_lshl_add_u64 v[4:5], v[132:133], 0, v[4:5]
	s_mov_b32 m0, s28
	v_readfirstlane_b32 s28, v3
	global_load_lds_dwordx4 v[4:5], off
	v_lshl_add_u64 v[4:5], v[134:135], 0, v[0:1]
	s_mov_b32 m0, s28
	v_lshrrev_b32_e32 v146, 4, v143
	global_load_lds_dwordx4 v[4:5], off
	v_lshl_add_u64 v[4:5], v[136:137], 0, v[0:1]
	v_add_u32_e32 v0, 0x6000, v9
	v_and_b32_e32 v145, 15, v142
	v_readfirstlane_b32 s28, v0
	s_mov_b32 m0, s28
	v_lshlrev_b32_e32 v0, 1, v2
; template <int EPI>
; DI void gemm_tile(const GemmArgs& ga, const EpiArgs& ea, int m0, int n0, char* lds) {
;     ...
; #pragma unroll
;   for (int i = 0; i < 8; ++i)
; #pragma unroll
;     for (int j = 0; j < 4; ++j) acc[i][j] = f32x4{0.f, 0.f, 0.f, 0.f};
;   const int K = ga.K, nk = K >> 5;
;   float rowsum = 0.f;
;   if constexpr (EPI == EPI_INPROJ) rowsum = sum16(ea.rowss, m0 + tid);
;   const int prow = lane >> 2, pch = lane & 3;
;   const bf16_t* gsrc[6];
;   int ldsoff[6];
; #pragma unroll
;   for (int i = 0; i < 6; ++i) {
;     const int pi = w * 6 + i;
;     if (pi < 16) {
;       const int row = pi * 16 + prow;
;       gsrc[i] = ga.A + (size_t)(m0 + row) * ga.lda + swz64(row, pch) * 8;
;       ldsoff[i] = pi * 1024 + lane * 16;
;     } else {
;       const int row = (pi - 16) * 16 + prow;
;       gsrc[i] = ga.Bt + (size_t)(n0 + row) * K + swz64(row, pch) * 8;
;       ldsoff[i] = pi * 1024 + lane * 16;
;     }
;   }
;   auto dma = [&](int kt, int buf) {
;     const int k0 = kt << 5;
;     const int ac = ga.mix ? mixcol(k0) : k0;
;     char* base = lds + buf * 24576;
; #pragma unroll
;     for (int i = 0; i < 6; ++i) {
;       const int pi = w * 6 + i;
;       __builtin_amdgcn_global_load_lds((const unsigned*)(gsrc[i] + ((pi < 16) ? ac : k0)), (unsigned*)(base + ldsoff[i]), 16, 0, 0);
;     }
;   };
;   __syncthreads();
;   dma(0, 0);
;   if (nk > 1) dma(1, 1);
;   for (int kt = 0; kt < nk; ++kt) {
;     if (kt + 1 < nk) asm volatile("s_waitcnt vmcnt(6)" ::: "memory");
;     else asm volatile("s_waitcnt vmcnt(0)" ::: "memory");
;     __builtin_amdgcn_s_barrier();
;     const char* Ab = lds + (kt % 3) * 24576 + wm * 128 * 64;
;     const char* Bb = lds + (kt % 3) * 24576 + 16384 + wn * 64 * 64;
;     bf16x8 af[8], bfr[4];
;     const int ch = swz64(c16, quad) << 4;
; #pragma unroll
;     for (int nt = 0; nt < 4; ++nt) bfr[nt] = *(const bf16x8*)(Bb + (nt * 16 + c16) * 64 + ch);
; #pragma unroll
;     for (int mt = 0; mt < 2; ++mt) af[mt] = *(const bf16x8*)(Ab + (mt * 16 + c16) * 64 + ch);
;     __builtin_amdgcn_sched_barrier(0);
;     if (kt + 2 < nk) dma(kt + 2, (kt + 2) % 3);
	global_load_lds_dwordx4 v[4:5], off
	v_add_u32_e32 v4, 0x6000, v6
	v_lshl_add_u64 v[2:3], v[138:139], 0, v[0:1]
	v_readfirstlane_b32 s28, v4
	s_mov_b32 m0, s28
	v_lshlrev_b32_e32 v166, 12, v144
	global_load_lds_dwordx4 v[2:3], off
	v_lshl_add_u64 v[2:3], v[140:141], 0, v[0:1]
	v_add_u32_e32 v0, 0x6000, v10
	v_lshlrev_b32_e32 v162, 6, v145
	v_readfirstlane_b32 s28, v0
	s_mov_b32 m0, s28
	v_lshlrev_b32_e32 v0, 6, v142
	global_load_lds_dwordx4 v[2:3], off
	v_and_b32_e32 v165, 0xffffe000, v0
	v_and_b32_e32 v0, 12, v142
	v_lshrrev_b32_e64 v0, v0, s34
	v_bitop3_b32 v0, v0, v146, 3 bitop3:0x6c
	v_lshlrev_b32_e32 v161, 4, v0
	v_mov_b32_e32 v2, 0
	s_mov_b32 s26, 0
	s_mov_b32 s27, 64
	v_or_b32_e32 v167, v161, v162
	v_add_u32_e32 v164, 16, v166
	v_add_u32_e32 v163, 16, v165
	s_mov_b32 s28, 2
	s_mov_b32 s29, 0
	v_mov_b32_e32 v3, v2
	v_mov_b32_e32 v4, v2
	v_mov_b32_e32 v5, v2
	v_mov_b32_e32 v6, v2
	v_mov_b32_e32 v7, v2
	v_mov_b32_e32 v8, v2
	v_mov_b32_e32 v9, v2
	v_mov_b32_e32 v10, v2
	v_mov_b32_e32 v11, v2
	v_mov_b32_e32 v12, v2
	v_mov_b32_e32 v13, v2
	v_mov_b32_e32 v14, v2
	v_mov_b32_e32 v15, v2
	v_mov_b32_e32 v16, v2
	v_mov_b32_e32 v17, v2
	v_mov_b32_e32 v18, v2
	v_mov_b32_e32 v19, v2
	v_mov_b32_e32 v20, v2
	v_mov_b32_e32 v21, v2
	v_mov_b32_e32 v22, v2
	v_mov_b32_e32 v23, v2
	v_mov_b32_e32 v24, v2
	v_mov_b32_e32 v25, v2
	v_mov_b32_e32 v26, v2
	v_mov_b32_e32 v27, v2
	v_mov_b32_e32 v28, v2
	v_mov_b32_e32 v29, v2
	v_mov_b32_e32 v30, v2
	v_mov_b32_e32 v31, v2
	v_mov_b32_e32 v32, v2
	v_mov_b32_e32 v33, v2
	v_mov_b32_e32 v34, v2
	v_mov_b32_e32 v35, v2
	v_mov_b32_e32 v36, v2
	v_mov_b32_e32 v37, v2
	v_mov_b32_e32 v38, v2
	v_mov_b32_e32 v39, v2
	v_mov_b32_e32 v40, v2
	v_mov_b32_e32 v41, v2
	v_mov_b32_e32 v42, v2
	v_mov_b32_e32 v43, v2
	v_mov_b32_e32 v44, v2
	v_mov_b32_e32 v45, v2
	v_mov_b32_e32 v46, v2
	v_mov_b32_e32 v47, v2
	v_mov_b32_e32 v48, v2
	v_mov_b32_e32 v49, v2
	v_mov_b32_e32 v50, v2
	v_mov_b32_e32 v51, v2
	v_mov_b32_e32 v52, v2
	v_mov_b32_e32 v53, v2
	v_mov_b32_e32 v54, v2
	v_mov_b32_e32 v55, v2
	v_mov_b32_e32 v56, v2
	v_mov_b32_e32 v57, v2
	v_mov_b32_e32 v58, v2
	v_mov_b32_e32 v59, v2
	v_mov_b32_e32 v60, v2
	v_mov_b32_e32 v61, v2
	v_mov_b32_e32 v62, v2
	v_mov_b32_e32 v63, v2
	v_mov_b32_e32 v64, v2
	v_mov_b32_e32 v65, v2
	v_mov_b32_e32 v66, v2
	v_mov_b32_e32 v67, v2
	v_mov_b32_e32 v68, v2
	v_mov_b32_e32 v69, v2
	v_mov_b32_e32 v70, v2
	v_mov_b32_e32 v71, v2
	v_mov_b32_e32 v72, v2
	v_mov_b32_e32 v73, v2
	v_mov_b32_e32 v74, v2
	v_mov_b32_e32 v75, v2
	v_mov_b32_e32 v76, v2
	v_mov_b32_e32 v77, v2
	v_mov_b32_e32 v86, v2
	v_mov_b32_e32 v87, v2
	v_mov_b32_e32 v88, v2
	v_mov_b32_e32 v89, v2
	v_mov_b32_e32 v98, v2
	v_mov_b32_e32 v99, v2
	v_mov_b32_e32 v100, v2
	v_mov_b32_e32 v101, v2
	v_mov_b32_e32 v106, v2
	v_mov_b32_e32 v107, v2
	v_mov_b32_e32 v108, v2
	v_mov_b32_e32 v109, v2
	v_mov_b32_e32 v114, v2
	v_mov_b32_e32 v115, v2
	v_mov_b32_e32 v116, v2
	v_mov_b32_e32 v117, v2
	v_mov_b32_e32 v118, v2
	v_mov_b32_e32 v119, v2
	v_mov_b32_e32 v120, v2
	v_mov_b32_e32 v121, v2
	v_mov_b32_e32 v122, v2
	v_mov_b32_e32 v123, v2
	v_mov_b32_e32 v124, v2
	v_mov_b32_e32 v125, v2
	v_mov_b32_e32 v126, v2
	v_mov_b32_e32 v127, v2
	v_mov_b32_e32 v128, v2
	v_mov_b32_e32 v129, v2
	v_mov_b32_e32 v78, v2
	v_mov_b32_e32 v79, v2
	v_mov_b32_e32 v80, v2
	v_mov_b32_e32 v81, v2
	v_mov_b32_e32 v82, v2
	v_mov_b32_e32 v83, v2
	v_mov_b32_e32 v84, v2
	v_mov_b32_e32 v85, v2
	v_mov_b32_e32 v90, v2
	v_mov_b32_e32 v91, v2
	v_mov_b32_e32 v92, v2
	v_mov_b32_e32 v93, v2
	v_mov_b32_e32 v94, v2
	v_mov_b32_e32 v95, v2
	v_mov_b32_e32 v96, v2
	v_mov_b32_e32 v97, v2
	v_mov_b32_e32 v102, v2
	v_mov_b32_e32 v103, v2
	v_mov_b32_e32 v104, v2
	v_mov_b32_e32 v105, v2
	v_mov_b32_e32 v110, v2
	v_mov_b32_e32 v111, v2
	v_mov_b32_e32 v112, v2
	v_mov_b32_e32 v113, v2
.LBB0_1541:
	s_mul_hi_u32 s34, s29, 0xaaaaaaab
	s_lshr_b32 s34, s34, 1
	v_add_u32_e32 v0, s26, v167
	s_mul_i32 s34, s34, 0xfffee000
	v_add3_u32 v196, v164, s34, v0
	s_waitcnt vmcnt(6)
	s_barrier
	v_add3_u32 v212, v163, s34, v0
	ds_read_b128 v[168:171], v196 offset:16384
	ds_read_b128 v[188:191], v196 offset:17408
	ds_read_b128 v[192:195], v196 offset:18432
	ds_read_b128 v[196:199], v196 offset:19456
	ds_read_b128 v[200:203], v212
	ds_read_b128 v[204:207], v212 offset:1024
	s_add_i32 s29, s29, 1
	s_add_i32 s34, s28, -2
	s_mul_i32 s38, s28, 0xab
	s_bfe_u32 s38, s38, 0x70009
	s_mul_i32 s38, s38, 3
	s_sub_i32 s38, s28, s38
	s_and_b32 s38, s38, 0xff
	s_lshr_b32 s39, s28, 4
	s_cmp_eq_u32 s39, 2
	s_movk_i32 s40, 0xc00
	s_cselect_b32 s40, s40, 0x1000
	s_cmp_lg_u32 s39, 1
	s_cselect_b32 s39, s40, 0x800
	s_cmp_gt_u32 s34, 13
	s_cselect_b32 s34, s39, 0x200
	s_and_b32 s39, s27, 0x1e0
	s_or_b32 s34, s34, s39
	s_mulk_i32 s38, 0x6000
	v_mov_b32_e32 v213, s27
	v_mov_b32_e32 v214, s34
	s_add_i32 s38, s38, 16
	s_add_i32 s34, s38, s101
	v_cndmask_b32_e32 v0, v213, v214, vcc
	v_lshlrev_b64 v[208:209], 1, v[0:1]
	s_mov_b32 m0, s34
	v_lshl_add_u64 v[210:211], v[130:131], 0, v[208:209]
	global_load_lds_dwordx4 v[210:211], off
	v_cndmask_b32_e64 v0, v213, v214, s[0:1]
	s_add_i32 m0, s34, 0x400
	v_lshl_add_u64 v[210:211], v[0:1], 1, v[132:133]
	global_load_lds_dwordx4 v[210:211], off
	s_add_i32 m0, s34, 0x800
	v_lshl_add_u64 v[210:211], v[134:135], 0, v[208:209]
	global_load_lds_dwordx4 v[210:211], off
	s_add_i32 m0, s34, 0xc00
	v_lshl_add_u64 v[210:211], v[136:137], 0, v[208:209]
	global_load_lds_dwordx4 v[210:211], off
	v_cndmask_b32_e64 v0, v213, v214, s[36:37]
	v_lshlrev_b64 v[208:209], 1, v[0:1]
	s_add_i32 m0, s34, 0x1000
	v_lshl_add_u64 v[210:211], v[138:139], 0, v[208:209]
	global_load_lds_dwordx4 v[210:211], off
	s_add_i32 m0, s34, 0x1400
	v_lshl_add_u64 v[208:209], v[140:141], 0, v[208:209]
	global_load_lds_dwordx4 v[208:209], off
	s_waitcnt lgkmcnt(0)
; #define MFMA16(a, b, c) __builtin_amdgcn_mfma_f32_16x16x32_bf16((a), (b), (c), 0, 0, 0)
; template <int EPI>
; DI void gemm_tile(const GemmArgs& ga, const EpiArgs& ea, int m0, int n0, char* lds) {
;     ...
;   for (int kt = 0; kt < nk; ++kt) {
;     if (kt + 1 < nk) asm volatile("s_waitcnt vmcnt(6)" ::: "memory");
;     else asm volatile("s_waitcnt vmcnt(0)" ::: "memory");
;     __builtin_amdgcn_s_barrier();
;     const char* Ab = lds + (kt % 3) * 24576 + wm * 128 * 64;
;     const char* Bb = lds + (kt % 3) * 24576 + 16384 + wn * 64 * 64;
;     bf16x8 af[8], bfr[4];
;     const int ch = swz64(c16, quad) << 4;
; #pragma unroll
;     for (int nt = 0; nt < 4; ++nt) bfr[nt] = *(const bf16x8*)(Bb + (nt * 16 + c16) * 64 + ch);
; #pragma unroll
;     for (int mt = 0; mt < 2; ++mt) af[mt] = *(const bf16x8*)(Ab + (mt * 16 + c16) * 64 + ch);
;     __builtin_amdgcn_sched_barrier(0);
;     if (kt + 2 < nk) dma(kt + 2, (kt + 2) % 3);
;     __builtin_amdgcn_sched_barrier(0);
; #pragma unroll
;     for (int g = 0; g < 4; ++g) {
;       if (g < 3) {
; #pragma unroll
;         for (int mt = 2 * g + 2; mt < 2 * g + 4; ++mt) af[mt] = *(const bf16x8*)(Ab + (mt * 16 + c16) * 64 + ch);
;       }
; #pragma unroll
;       for (int mt = 2 * g; mt < 2 * g + 2; ++mt)
; #pragma unroll
;         for (int nt = 0; nt < 4; ++nt) acc[mt][nt] = MFMA16(bfr[nt], af[mt], acc[mt][nt]);
;       __builtin_amdgcn_sched_barrier(0);
;     }
;   }
	v_mfma_f32_16x16x32_bf16 v[126:129], v[168:171], v[200:203], v[126:129]
	v_mfma_f32_16x16x32_bf16 v[122:125], v[188:191], v[200:203], v[122:125]
	v_mfma_f32_16x16x32_bf16 v[118:121], v[192:195], v[200:203], v[118:121]
	v_mfma_f32_16x16x32_bf16 v[114:117], v[196:199], v[200:203], v[114:117]
	ds_read_b128 v[200:203], v212 offset:2048
	ds_read_b128 v[208:211], v212 offset:3072
	v_mfma_f32_16x16x32_bf16 v[106:109], v[168:171], v[204:207], v[106:109]
	v_mfma_f32_16x16x32_bf16 v[98:101], v[188:191], v[204:207], v[98:101]
	v_mfma_f32_16x16x32_bf16 v[86:89], v[192:195], v[204:207], v[86:89]
	v_mfma_f32_16x16x32_bf16 v[74:77], v[196:199], v[204:207], v[74:77]
	s_waitcnt lgkmcnt(0)
	v_mfma_f32_16x16x32_bf16 v[70:73], v[168:171], v[200:203], v[70:73]
	v_mfma_f32_16x16x32_bf16 v[66:69], v[188:191], v[200:203], v[66:69]
	v_mfma_f32_16x16x32_bf16 v[62:65], v[192:195], v[200:203], v[62:65]
	v_mfma_f32_16x16x32_bf16 v[58:61], v[196:199], v[200:203], v[58:61]
	ds_read_b128 v[200:203], v212 offset:4096
	ds_read_b128 v[204:207], v212 offset:5120
	v_mfma_f32_16x16x32_bf16 v[54:57], v[168:171], v[208:211], v[54:57]
	v_mfma_f32_16x16x32_bf16 v[50:53], v[188:191], v[208:211], v[50:53]
	v_mfma_f32_16x16x32_bf16 v[46:49], v[192:195], v[208:211], v[46:49]
	v_mfma_f32_16x16x32_bf16 v[42:45], v[196:199], v[208:211], v[42:45]
	s_waitcnt lgkmcnt(0)
	v_mfma_f32_16x16x32_bf16 v[38:41], v[168:171], v[200:203], v[38:41]
	v_mfma_f32_16x16x32_bf16 v[34:37], v[188:191], v[200:203], v[34:37]
	v_mfma_f32_16x16x32_bf16 v[30:33], v[192:195], v[200:203], v[30:33]
	v_mfma_f32_16x16x32_bf16 v[26:29], v[196:199], v[200:203], v[26:29]
	ds_read_b128 v[200:203], v212 offset:6144
	ds_read_b128 v[208:211], v212 offset:7168
	v_mfma_f32_16x16x32_bf16 v[22:25], v[168:171], v[204:207], v[22:25]
	v_mfma_f32_16x16x32_bf16 v[18:21], v[188:191], v[204:207], v[18:21]
	v_mfma_f32_16x16x32_bf16 v[14:17], v[192:195], v[204:207], v[14:17]
	v_mfma_f32_16x16x32_bf16 v[10:13], v[196:199], v[204:207], v[10:13]
	s_waitcnt lgkmcnt(0)
	v_mfma_f32_16x16x32_bf16 v[6:9], v[168:171], v[200:203], v[6:9]
	v_mfma_f32_16x16x32_bf16 v[2:5], v[188:191], v[200:203], v[2:5]
	v_mfma_f32_16x16x32_bf16 v[78:81], v[192:195], v[200:203], v[78:81]
	v_mfma_f32_16x16x32_bf16 v[82:85], v[196:199], v[200:203], v[82:85]
	v_mfma_f32_16x16x32_bf16 v[90:93], v[168:171], v[208:211], v[90:93]
	v_mfma_f32_16x16x32_bf16 v[94:97], v[188:191], v[208:211], v[94:97]
	v_mfma_f32_16x16x32_bf16 v[102:105], v[192:195], v[208:211], v[102:105]
	v_mfma_f32_16x16x32_bf16 v[110:113], v[196:199], v[208:211], v[110:113]
	s_add_i32 s28, s28, 1
	s_add_i32 s27, s27, 32
	s_addk_i32 s26, 0x6000
	s_cmp_eq_u32 s26, 0x174000
	s_cbranch_scc0 .LBB0_1541
	s_add_i32 s0, 16, 0xc000
	v_add_u32_e32 v0, s0, v166
	v_add3_u32 v0, v0, v161, v162
	s_waitcnt vmcnt(6)
	s_barrier
	ds_read_b128 v[130:133], v0 offset:16384
	ds_read_b128 v[134:137], v0 offset:17408
	ds_read_b128 v[138:141], v0 offset:18432
	ds_read_b128 v[156:159], v0 offset:19456
	v_add_u32_e32 v0, s0, v165
	v_add3_u32 v0, v0, v161, v162
	ds_read_b128 v[166:169], v0
	ds_read_b128 v[188:191], v0 offset:1024
	s_waitcnt lgkmcnt(0)
	v_mfma_f32_16x16x32_bf16 v[126:129], v[130:133], v[166:169], v[126:129]
	v_mfma_f32_16x16x32_bf16 v[122:125], v[134:137], v[166:169], v[122:125]
	v_mfma_f32_16x16x32_bf16 v[118:121], v[138:141], v[166:169], v[118:121]
	v_mfma_f32_16x16x32_bf16 v[114:117], v[156:159], v[166:169], v[114:117]
	ds_read_b128 v[166:169], v0 offset:2048
	ds_read_b128 v[192:195], v0 offset:3072
	v_mfma_f32_16x16x32_bf16 v[106:109], v[130:133], v[188:191], v[106:109]
	v_mfma_f32_16x16x32_bf16 v[98:101], v[134:137], v[188:191], v[98:101]
	v_mfma_f32_16x16x32_bf16 v[86:89], v[138:141], v[188:191], v[86:89]
	v_mfma_f32_16x16x32_bf16 v[74:77], v[156:159], v[188:191], v[74:77]
	s_waitcnt lgkmcnt(0)
	v_mfma_f32_16x16x32_bf16 v[70:73], v[130:133], v[166:169], v[70:73]
	v_mfma_f32_16x16x32_bf16 v[66:69], v[134:137], v[166:169], v[66:69]
	v_mfma_f32_16x16x32_bf16 v[62:65], v[138:141], v[166:169], v[62:65]
	v_mfma_f32_16x16x32_bf16 v[58:61], v[156:159], v[166:169], v[58:61]
	ds_read_b128 v[166:169], v0 offset:4096
	ds_read_b128 v[188:191], v0 offset:5120
	v_mfma_f32_16x16x32_bf16 v[54:57], v[130:133], v[192:195], v[54:57]
	v_mfma_f32_16x16x32_bf16 v[50:53], v[134:137], v[192:195], v[50:53]
	v_mfma_f32_16x16x32_bf16 v[46:49], v[138:141], v[192:195], v[46:49]
	v_mfma_f32_16x16x32_bf16 v[42:45], v[156:159], v[192:195], v[42:45]
	s_waitcnt lgkmcnt(0)
	v_mfma_f32_16x16x32_bf16 v[38:41], v[130:133], v[166:169], v[38:41]
	v_mfma_f32_16x16x32_bf16 v[34:37], v[134:137], v[166:169], v[34:37]
	v_mfma_f32_16x16x32_bf16 v[30:33], v[138:141], v[166:169], v[30:33]
	v_mfma_f32_16x16x32_bf16 v[26:29], v[156:159], v[166:169], v[26:29]
	ds_read_b128 v[166:169], v0 offset:6144
	ds_read_b128 v[192:195], v0 offset:7168
	v_mfma_f32_16x16x32_bf16 v[22:25], v[130:133], v[188:191], v[22:25]
	v_mfma_f32_16x16x32_bf16 v[18:21], v[134:137], v[188:191], v[18:21]
	v_mfma_f32_16x16x32_bf16 v[14:17], v[138:141], v[188:191], v[14:17]
	v_mfma_f32_16x16x32_bf16 v[10:13], v[156:159], v[188:191], v[10:13]
	s_waitcnt lgkmcnt(0)
	v_mfma_f32_16x16x32_bf16 v[6:9], v[130:133], v[166:169], v[6:9]
	v_mfma_f32_16x16x32_bf16 v[2:5], v[134:137], v[166:169], v[2:5]
	v_mfma_f32_16x16x32_bf16 v[188:191], v[138:141], v[166:169], v[78:81]
	v_mfma_f32_16x16x32_bf16 v[166:169], v[156:159], v[166:169], v[82:85]
	v_mfma_f32_16x16x32_bf16 v[130:133], v[130:133], v[192:195], v[90:93]
	v_mfma_f32_16x16x32_bf16 v[134:137], v[134:137], v[192:195], v[94:97]
	v_mfma_f32_16x16x32_bf16 v[138:141], v[138:141], v[192:195], v[102:105]
	v_mfma_f32_16x16x32_bf16 v[156:159], v[156:159], v[192:195], v[110:113]
	v_add3_u32 v0, v164, v161, v162
	s_waitcnt vmcnt(0)
	s_barrier
; #define MFMA16(a, b, c) __builtin_amdgcn_mfma_f32_16x16x32_bf16((a), (b), (c), 0, 0, 0)
; template <int EPI>
; DI void gemm_tile(const GemmArgs& ga, const EpiArgs& ea, int m0, int n0, char* lds) {
;     ...
;     const char* Ab = lds + (kt % 3) * 24576 + wm * 128 * 64;
;     const char* Bb = lds + (kt % 3) * 24576 + 16384 + wn * 64 * 64;
;     bf16x8 af[8], bfr[4];
;     const int ch = swz64(c16, quad) << 4;
; #pragma unroll
;     for (int nt = 0; nt < 4; ++nt) bfr[nt] = *(const bf16x8*)(Bb + (nt * 16 + c16) * 64 + ch);
; #pragma unroll
;     for (int mt = 0; mt < 2; ++mt) af[mt] = *(const bf16x8*)(Ab + (mt * 16 + c16) * 64 + ch);
;     __builtin_amdgcn_sched_barrier(0);
;     if (kt + 2 < nk) dma(kt + 2, (kt + 2) % 3);
;     __builtin_amdgcn_sched_barrier(0);
; #pragma unroll
;     for (int g = 0; g < 4; ++g) {
;       if (g < 3) {
; #pragma unroll
;         for (int mt = 2 * g + 2; mt < 2 * g + 4; ++mt) af[mt] = *(const bf16x8*)(Ab + (mt * 16 + c16) * 64 + ch);
;       }
; #pragma unroll
;       for (int mt = 2 * g; mt < 2 * g + 2; ++mt)
; #pragma unroll
;         for (int nt = 0; nt < 4; ++nt) acc[mt][nt] = MFMA16(bfr[nt], af[mt], acc[mt][nt]);
;     ...
;   } else {
; #pragma unroll
;     for (int mt = 0; mt < 8; ++mt) {
;       const int row = m0 + wm * 128 + mt * 16 + c16;
;       float ss = 0.f;
; #pragma unroll
;       for (int nt = 0; nt < 4; ++nt) {
;         const int col0 = n0 + wn * 64 + nt * 16 + quad * 4;
;         const size_t idx = (size_t)row * 1024 + col0;
;         float4 xo;
;         if (ea.xsrc) xo = *(const float4*)(ea.xsrc + idx);
;         else {
;           const uint2 u = *(const uint2*)(p.xb + idx);
;           xo = make_float4(__uint_as_float(u.x << 16), __uint_as_float(u.x & 0xffff0000u), __uint_as_float(u.y << 16), __uint_as_float(u.y & 0xffff0000u));
;         }
;         float4 xn;
;         xn.x = xo.x + acc[mt][nt][0]; xn.y = xo.y + acc[mt][nt][1]; xn.z = xo.z + acc[mt][nt][2]; xn.w = xo.w + acc[mt][nt][3];
;         ss += xn.x * xn.x + xn.y * xn.y + xn.z * xn.z + xn.w * xn.w;
;         {
;           uint2 o; o.x = pack2(xn.x, xn.y); o.y = pack2(xn.z, xn.w);
;           *(uint2*)(p.xb + idx) = o;
;         }
;       }
;       ss = quadsum(ss);
;       if (quad == 0) ea.rowss_next[(size_t)((n0 >> 7) * 2 + wn) * NT + row] = ss;
;     }
	ds_read_b128 v[192:195], v0 offset:16384
	ds_read_b128 v[196:199], v0 offset:17408
	ds_read_b128 v[200:203], v0 offset:18432
	ds_read_b128 v[204:207], v0 offset:19456
	v_add3_u32 v0, v163, v161, v162
	ds_read_b128 v[78:81], v0
	ds_read_b128 v[82:85], v0 offset:1024
	s_waitcnt lgkmcnt(0)
	v_mfma_f32_16x16x32_bf16 v[160:163], v[192:195], v[78:81], v[126:129]
	v_mfma_f32_16x16x32_bf16 v[208:211], v[196:199], v[78:81], v[122:125]
	v_mfma_f32_16x16x32_bf16 v[118:121], v[200:203], v[78:81], v[118:121]
	v_mfma_f32_16x16x32_bf16 v[114:117], v[204:207], v[78:81], v[114:117]
	ds_read_b128 v[78:81], v0 offset:2048
	ds_read_b128 v[122:125], v0 offset:3072
	v_mfma_f32_16x16x32_bf16 v[110:113], v[192:195], v[82:85], v[106:109]
	v_mfma_f32_16x16x32_bf16 v[106:109], v[196:199], v[82:85], v[98:101]
	v_mfma_f32_16x16x32_bf16 v[102:105], v[200:203], v[82:85], v[86:89]
	v_mfma_f32_16x16x32_bf16 v[98:101], v[204:207], v[82:85], v[74:77]
	s_waitcnt lgkmcnt(0)
	v_mfma_f32_16x16x32_bf16 v[94:97], v[192:195], v[78:81], v[70:73]
	v_mfma_f32_16x16x32_bf16 v[70:73], v[200:203], v[122:125], v[46:49]
	s_nop 2
	ds_read_b128 v[46:49], v0 offset:4096
	ds_read_b128 v[126:129], v0 offset:5120
	v_mfma_f32_16x16x32_bf16 v[90:93], v[196:199], v[78:81], v[66:69]
	v_mfma_f32_16x16x32_bf16 v[86:89], v[200:203], v[78:81], v[62:65]
	v_mfma_f32_16x16x32_bf16 v[82:85], v[204:207], v[78:81], v[58:61]
	v_mfma_f32_16x16x32_bf16 v[78:81], v[192:195], v[122:125], v[54:57]
	v_mfma_f32_16x16x32_bf16 v[74:77], v[196:199], v[122:125], v[50:53]
	v_mfma_f32_16x16x32_bf16 v[66:69], v[204:207], v[122:125], v[42:45]
	s_waitcnt lgkmcnt(0)
	v_mfma_f32_16x16x32_bf16 v[62:65], v[192:195], v[46:49], v[38:41]
	v_mfma_f32_16x16x32_bf16 v[38:41], v[200:203], v[126:129], v[14:17]
	s_nop 2
	ds_read_b128 v[14:17], v0 offset:6144
	ds_read_b128 v[122:125], v0 offset:7168
	v_mfma_f32_16x16x32_bf16 v[58:61], v[196:199], v[46:49], v[34:37]
	v_mfma_f32_16x16x32_bf16 v[54:57], v[200:203], v[46:49], v[30:33]
	v_mfma_f32_16x16x32_bf16 v[50:53], v[204:207], v[46:49], v[26:29]
	v_mfma_f32_16x16x32_bf16 v[46:49], v[192:195], v[126:129], v[22:25]
	v_mfma_f32_16x16x32_bf16 v[42:45], v[196:199], v[126:129], v[18:21]
	v_mfma_f32_16x16x32_bf16 v[34:37], v[204:207], v[126:129], v[10:13]
	s_waitcnt lgkmcnt(0)
	v_mfma_f32_16x16x32_bf16 v[30:33], v[192:195], v[14:17], v[6:9]
	v_mfma_f32_16x16x32_bf16 v[26:29], v[196:199], v[14:17], v[2:5]
	v_mfma_f32_16x16x32_bf16 v[22:25], v[200:203], v[14:17], v[188:191]
	v_mfma_f32_16x16x32_bf16 v[18:21], v[204:207], v[14:17], v[166:169]
	v_mfma_f32_16x16x32_bf16 v[14:17], v[192:195], v[122:125], v[130:133]
	v_mfma_f32_16x16x32_bf16 v[10:13], v[196:199], v[122:125], v[134:137]
	v_mfma_f32_16x16x32_bf16 v[6:9], v[200:203], v[122:125], v[138:141]
	v_mfma_f32_16x16x32_bf16 v[2:5], v[204:207], v[122:125], v[156:159]
	v_and_b32_e32 v0, 0xffffff80, v142
	v_add_u32_e32 v0, s23, v0
	v_or_b32_e32 v124, v0, v145
	v_lshlrev_b32_e32 v0, 6, v144
	v_lshlrev_b32_e32 v122, 2, v146
	v_ashrrev_i32_e32 v125, 31, v124
	v_or3_b32 v122, v0, v122, s22
	v_lshlrev_b64 v[128:129], 11, v[124:125]
	v_ashrrev_i32_e32 v123, 31, v122
	v_lshl_add_u64 v[128:129], s[50:51], 0, v[128:129]
	v_lshl_add_u64 v[128:129], v[122:123], 1, v[128:129]
	global_load_dwordx2 v[130:131], v[128:129], off
	v_lshl_or_b32 v126, s8, 1, v144
	v_ashrrev_i32_e32 v127, 31, v126
	v_lshlrev_b64 v[126:127], 17, v[126:127]
	v_cmp_gt_u32_e32 vcc, 16, v143
	s_waitcnt vmcnt(0)
	v_lshlrev_b32_e32 v132, 16, v130
	v_and_b32_e32 v133, 0xffff0000, v130
	v_pk_add_f32 v[132:133], v[160:161], v[132:133]
	v_lshlrev_b32_e32 v130, 16, v131
	v_and_b32_e32 v131, 0xffff0000, v131
	v_mul_f32_e32 v0, v133, v133
	v_pk_add_f32 v[130:131], v[162:163], v[130:131]
	v_pk_fma_f32 v[134:135], v[132:133], v[132:133], v[0:1] op_sel_hi:[1,1,0]
	v_mul_f32_e32 v0, v131, v131
	v_pk_fma_f32 v[134:135], v[130:131], v[130:131], v[134:135]
	v_cvt_pk_bf16_f32 v132, v132, v133
	v_cvt_pk_bf16_f32 v133, v130, v131
	global_load_dwordx2 v[130:131], v[128:129], off offset:32
	v_pk_add_f32 v[134:135], v[0:1], v[134:135] op_sel_hi:[0,1]
	global_store_dwordx2 v[128:129], v[132:133], off
	s_waitcnt vmcnt(1)
	v_lshlrev_b32_e32 v132, 16, v130
	v_and_b32_e32 v133, 0xffff0000, v130
	v_pk_add_f32 v[132:133], v[208:209], v[132:133]
	v_lshlrev_b32_e32 v130, 16, v131
	v_and_b32_e32 v131, 0xffff0000, v131
	v_mul_f32_e32 v0, v133, v133
	v_pk_add_f32 v[130:131], v[210:211], v[130:131]
	v_pk_fma_f32 v[136:137], v[132:133], v[132:133], v[0:1] op_sel_hi:[1,1,0]
	v_mul_f32_e32 v0, v131, v131
	v_pk_fma_f32 v[136:137], v[130:131], v[130:131], v[136:137]
	v_cvt_pk_bf16_f32 v132, v132, v133
	v_cvt_pk_bf16_f32 v133, v130, v131
	global_load_dwordx2 v[130:131], v[128:129], off offset:64
	v_pk_add_f32 v[136:137], v[0:1], v[136:137] op_sel_hi:[0,1]
	global_store_dwordx2 v[128:129], v[132:133], off offset:32
	v_pk_add_f32 v[134:135], v[134:135], v[136:137]
	s_waitcnt vmcnt(1)
	v_lshlrev_b32_e32 v132, 16, v130
	v_and_b32_e32 v133, 0xffff0000, v130
	v_lshlrev_b32_e32 v130, 16, v131
	v_and_b32_e32 v131, 0xffff0000, v131
	v_pk_add_f32 v[118:119], v[118:119], v[132:133]
	v_pk_add_f32 v[120:121], v[120:121], v[130:131]
	v_mul_f32_e32 v0, v119, v119
	v_pk_fma_f32 v[130:131], v[118:119], v[118:119], v[0:1] op_sel_hi:[1,1,0]
	v_cvt_pk_bf16_f32 v118, v118, v119
	v_cvt_pk_bf16_f32 v119, v120, v121
	global_store_dwordx2 v[128:129], v[118:119], off offset:64
	global_load_dwordx2 v[118:119], v[128:129], off offset:96
	v_pk_fma_f32 v[130:131], v[120:121], v[120:121], v[130:131]
	v_mul_f32_e32 v0, v121, v121
	v_pk_add_f32 v[130:131], v[0:1], v[130:131] op_sel_hi:[0,1]
	v_pk_add_f32 v[130:131], v[134:135], v[130:131]
	s_waitcnt vmcnt(0)
	v_lshlrev_b32_e32 v120, 16, v118
	v_and_b32_e32 v121, 0xffff0000, v118
	v_pk_add_f32 v[114:115], v[114:115], v[120:121]
	v_lshlrev_b32_e32 v118, 16, v119
	v_and_b32_e32 v119, 0xffff0000, v119
	v_mul_f32_e32 v0, v115, v115
	v_pk_add_f32 v[116:117], v[116:117], v[118:119]
	v_pk_fma_f32 v[118:119], v[114:115], v[114:115], v[0:1] op_sel_hi:[1,1,0]
	v_mul_f32_e32 v0, v117, v117
	v_pk_fma_f32 v[118:119], v[116:117], v[116:117], v[118:119]
	v_cvt_pk_bf16_f32 v114, v114, v115
	v_pk_add_f32 v[118:119], v[0:1], v[118:119] op_sel_hi:[0,1]
	v_pk_add_f32 v[118:119], v[130:131], v[118:119]
	v_cvt_pk_bf16_f32 v115, v116, v117
	v_mov_b32_e32 v0, v118
	s_nop 1
	v_permlane16_swap_b32_e32 v118, v0
	v_add_f32_e32 v0, v118, v0
	global_store_dwordx2 v[128:129], v[114:115], off offset:96
	v_mov_b32_e32 v116, v0
	v_lshl_add_u64 v[114:115], s[24:25], 0, v[126:127]
	s_nop 0
	v_permlane32_swap_b32_e32 v0, v116
	v_lshl_add_u64 v[114:115], v[124:125], 2, v[114:115]
	s_and_saveexec_b64 s[0:1], vcc
	s_cbranch_execz .LBB0_1544
	v_add_f32_e32 v0, v0, v116
	global_store_dword v[114:115], v0, off
